# prenorm: next row's loads issued at the top of the iteration (full-iteration prefetch distance)
# speedup vs baseline: 1.0028x; 1.0028x over previous
.LBB0_69:
	s_waitcnt vmcnt(4)
	v_mov_b32_e32 v56, v29
	v_mov_b32_e32 v57, v25
	v_ashrrev_i32_e32 v43, 12, v41
	v_mov_b32_e32 v54, v9
	v_mov_b32_e32 v55, v1
	v_pk_mul_f32 v[72:73], v[56:57], v[56:57]
	v_mul_i32_i24_e32 v56, 0xc00, v43
	v_mov_b32_e32 v52, v8
	v_mov_b32_e32 v53, v0
	v_pk_mul_f32 v[54:55], v[54:55], v[54:55]
	v_ashrrev_i32_e32 v57, 31, v56
	v_pk_fma_f32 v[74:75], v[52:53], v[52:53], v[54:55]
	v_lshl_add_u64 v[52:53], v[56:57], 2, s[38:39]
	v_lshl_add_u64 v[76:77], v[52:53], 0, s[8:9]
	v_lshl_add_u64 v[78:79], v[52:53], 0, v[32:33]
	v_lshl_add_u64 v[56:57], v[76:77], 0, v[32:33]
	global_load_dwordx4 v[52:55], v[78:79], off
	s_nop 0
	global_load_dwordx4 v[84:87], v[56:57], off
	global_load_dwordx4 v[88:91], v[56:57], off offset:1024
	global_load_dwordx4 v[92:95], v[78:79], off offset:1024
	global_load_dwordx4 v[96:99], v[56:57], off offset:2048
	global_load_dwordx4 v[100:103], v[78:79], off offset:2048
	global_load_dwordx4 v[104:107], v[56:57], off offset:3072
	global_load_dwordx4 v[108:111], v[78:79], off offset:3072
	v_add_u32_e32 v129, s88, v41
	v_cmp_gt_i32_e32 vcc, s10, v129
	v_cndmask_b32_e32 v132, v41, v129, vcc
	v_ashrrev_i32_e32 v133, 31, v132
	v_lshlrev_b64 v[132:133], 12, v[132:133]
	v_lshl_add_u64 v[132:133], v[34:35], 0, v[132:133]
	global_load_dwordx4 v[112:115], v[132:133], off nt
	global_load_dwordx4 v[116:119], v[132:133], off offset:1024 nt
	global_load_dwordx4 v[120:123], v[132:133], off offset:2048 nt
	global_load_dwordx4 v[124:127], v[132:133], off offset:3072 nt
	v_mov_b32_e32 v68, v28
	v_mov_b32_e32 v69, v24
	v_mov_b32_e32 v64, v30
	v_mov_b32_e32 v65, v26
	v_pk_fma_f32 v[68:69], v[68:69], v[68:69], v[72:73]
	v_mov_b32_e32 v60, v10
	v_mov_b32_e32 v61, v2
	v_add_u32_e32 v51, s88, v41
	v_mov_b32_e32 v66, v31
	v_mov_b32_e32 v67, v27
	v_pk_fma_f32 v[64:65], v[64:65], v[64:65], v[68:69]
	v_mov_b32_e32 v62, v11
	v_mov_b32_e32 v63, v3
	v_cmp_gt_i32_e32 vcc, s10, v51
	v_pk_fma_f32 v[60:61], v[60:61], v[60:61], v[74:75]
	v_pk_fma_f32 v[82:83], v[66:67], v[66:67], v[64:65]
	v_mov_b32_e32 v39, v33
	v_cndmask_b32_e32 v70, v41, v51, vcc
	v_pk_fma_f32 v[80:81], v[62:63], v[62:63], v[60:61]
	v_add_f32_e32 v41, v82, v83
	v_lshl_add_u64 v[82:83], v[76:77], 0, v[38:39]
	v_add_f32_e32 v39, v41, v80
	v_add_f32_e32 v39, v39, v81
	ds_bpermute_b32 v41, v44, v39
	v_ashrrev_i32_e32 v71, 31, v70
	v_lshlrev_b64 v[70:71], 12, v[70:71]
	v_lshl_add_u64 v[72:73], v[34:35], 0, v[70:71]
	s_waitcnt lgkmcnt(0)
	v_add_f32_e32 v39, v39, v41
	ds_bpermute_b32 v41, v45, v39
	v_mov_b32_e32 v43, v33
	s_waitcnt lgkmcnt(0)
	v_add_f32_e32 v39, v39, v41
	ds_bpermute_b32 v41, v46, v39
	s_waitcnt lgkmcnt(0)
	v_add_f32_e32 v39, v39, v41
	ds_bpermute_b32 v41, v47, v39
	s_waitcnt lgkmcnt(0)
	v_add_f32_e32 v39, v39, v41
	ds_bpermute_b32 v41, v48, v39
	s_waitcnt lgkmcnt(0)
	v_add_f32_e32 v39, v39, v41
	ds_bpermute_b32 v41, v49, v39
	s_waitcnt lgkmcnt(0)
	v_add_f32_e32 v39, v39, v41
	v_fmamk_f32 v39, v39, 0x3a800000, v50
	v_mul_f32_e32 v41, 0x4b800000, v39
	v_cmp_gt_f32_e32 vcc, s12, v39
	s_waitcnt vmcnt(4)
	v_pk_add_f32 v[56:57], v[84:85], 1.0 op_sel_hi:[1,0]
	v_cndmask_b32_e32 v39, v39, v41, vcc
	v_rsq_f32_e32 v39, v39
	v_pk_add_f32 v[58:59], v[86:87], 1.0 op_sel_hi:[1,0]
	v_mul_f32_e32 v41, 0x45800000, v39
	v_cndmask_b32_e32 v80, v39, v41, vcc
	v_pk_mul_f32 v[28:29], v[28:29], v[80:81] op_sel_hi:[1,0]
	v_pk_mul_f32 v[30:31], v[30:31], v[80:81] op_sel_hi:[1,0]
	v_pk_mul_f32 v[28:29], v[4:5], v[28:29]
	v_pk_mul_f32 v[30:31], v[6:7], v[30:31]
	v_pk_fma_f32 v[28:29], v[56:57], v[28:29], v[52:53]
	v_pk_fma_f32 v[30:31], v[58:59], v[30:31], v[54:55]
	v_cvt_pk_bf16_f32 v28, v28, v29
	v_cvt_pk_bf16_f32 v29, v30, v31
	global_store_dwordx2 v[36:37], v[28:29], off
	v_pk_mul_f32 v[24:25], v[24:25], v[80:81] op_sel_hi:[1,0]
	v_pk_mul_f32 v[26:27], v[26:27], v[80:81] op_sel_hi:[1,0]
	v_pk_mul_f32 v[24:25], v[12:13], v[24:25]
	v_pk_mul_f32 v[26:27], v[14:15], v[26:27]
	v_mov_b32_e32 v41, v33
	v_lshl_add_u64 v[56:57], v[76:77], 0, v[40:41]
	v_pk_mul_f32 v[8:9], v[8:9], v[80:81] op_sel_hi:[1,0]
	v_pk_mul_f32 v[10:11], v[10:11], v[80:81] op_sel_hi:[1,0]
	v_pk_mul_f32 v[8:9], v[16:17], v[8:9]
	v_pk_mul_f32 v[10:11], v[18:19], v[10:11]
	v_pk_mul_f32 v[0:1], v[0:1], v[80:81] op_sel_hi:[1,0]
	v_pk_mul_f32 v[2:3], v[2:3], v[80:81] op_sel_hi:[1,0]
	v_cmp_lt_i32_e32 vcc, s11, v51
	v_mov_b32_e32 v41, v51
	s_or_b64 s[6:7], vcc, s[6:7]
	v_pk_add_f32 v[28:29], v[88:89], 1.0 op_sel_hi:[1,0]
	v_pk_add_f32 v[30:31], v[90:91], 1.0 op_sel_hi:[1,0]
	v_pk_fma_f32 v[24:25], v[24:25], v[28:29], v[92:93]
	v_pk_fma_f32 v[26:27], v[26:27], v[30:31], v[94:95]
	v_cvt_pk_bf16_f32 v24, v24, v25
	v_cvt_pk_bf16_f32 v25, v26, v27
	global_store_dwordx2 v[36:37], v[24:25], off offset:512
	v_lshl_add_u64 v[52:53], v[76:77], 0, v[42:43]
	v_pk_mul_f32 v[76:77], v[20:21], v[0:1]
	v_pk_add_f32 v[24:25], v[96:97], 1.0 op_sel_hi:[1,0]
	v_pk_add_f32 v[26:27], v[98:99], 1.0 op_sel_hi:[1,0]
	v_pk_fma_f32 v[8:9], v[8:9], v[24:25], v[100:101]
	v_pk_fma_f32 v[10:11], v[10:11], v[26:27], v[102:103]
	v_cvt_pk_bf16_f32 v8, v8, v9
	v_cvt_pk_bf16_f32 v9, v10, v11
	global_store_dwordx2 v[36:37], v[8:9], off offset:1024
	v_pk_mul_f32 v[78:79], v[22:23], v[2:3]
	v_pk_add_f32 v[52:53], v[104:105], 1.0 op_sel_hi:[1,0]
	v_pk_add_f32 v[54:55], v[106:107], 1.0 op_sel_hi:[1,0]
	v_pk_fma_f32 v[52:53], v[76:77], v[52:53], v[108:109]
	v_pk_fma_f32 v[54:55], v[78:79], v[54:55], v[110:111]
	v_cvt_pk_bf16_f32 v52, v52, v53
	v_cvt_pk_bf16_f32 v53, v54, v55
	global_store_dwordx2 v[36:37], v[52:53], off offset:1536
	v_lshl_add_u64 v[36:37], v[36:37], 0, s[4:5]
	s_waitcnt vmcnt(4)
	v_mov_b32_e32 v0, v124
	v_mov_b32_e32 v1, v125
	v_mov_b32_e32 v30, v114
	v_mov_b32_e32 v31, v115
	v_mov_b32_e32 v28, v112
	v_mov_b32_e32 v29, v113
	v_mov_b32_e32 v26, v118
	v_mov_b32_e32 v27, v119
	v_mov_b32_e32 v24, v116
	v_mov_b32_e32 v25, v117
	v_mov_b32_e32 v10, v122
	v_mov_b32_e32 v11, v123
	v_mov_b32_e32 v8, v120
	v_mov_b32_e32 v9, v121
	v_mov_b32_e32 v2, v126
	v_mov_b32_e32 v3, v127
	s_andn2_b64 exec, exec, s[6:7]
	s_cbranch_execnz .LBB0_69
